# g2_scan_loader_waves_hand_written_lean
# speedup vs baseline: 1.0122x; 1.0122x over previous
.LBB0_1550:
	s_and_b64 vcc, exec, s[0:1]
	s_cbranch_vccz .LBB0_1544
	v_readlane_b32 s76, v253, 32
	s_mul_i32 s0, s4, 0x600
	s_add_i32 s76, s76, -2
	s_add_i32 s0, s0, s5
	s_and_b32 s77, s12, 3
	s_lshl_b32 s1, s0, 14
	s_lshl_b32 s8, s0, 13
	s_lshl_b32 s9, s76, 10
	s_lshl_b32 s10, s0, 2
	s_add_i32 s11, s9, s1
	s_add_i32 s11, s11, 0x4400000
	s_add_u32 s44, s34, s11
	s_addc_u32 s45, s35, 0
	s_add_i32 s11, s9, s1
	s_add_i32 s11, s11, 0x4401800
	s_add_u32 s46, s34, s11
	s_addc_u32 s47, s35, 0
	s_add_i32 s11, s9, s1
	s_mov_b32 s22, 0x4403000
	s_cmp_lt_u32 s76, 4
	s_cselect_b32 s22, s22, 0x73ff000
	s_add_i32 s11, s11, s22
	s_add_u32 s48, s34, s11
	s_addc_u32 s49, s35, 0
	s_add_i32 s11, s9, s1
	s_add_i32 s11, s11, 0x7400800
	s_add_u32 s50, s34, s11
	s_addc_u32 s51, s35, 0
	s_add_i32 s11, s9, s1
	s_add_i32 s11, s11, 0x7402000
	s_add_u32 s52, s34, s11
	s_addc_u32 s53, s35, 0
	s_add_i32 s11, s9, s1
	s_mov_b32 s22, 0x7403800
	s_cmp_lt_u32 s76, 2
	s_cselect_b32 s22, s22, 0x193ff800
	s_add_i32 s11, s11, s22
	s_add_u32 s54, s34, s11
	s_addc_u32 s55, s35, 0
	s_add_i32 s11, s9, s1
	s_add_i32 s11, s11, 0x19401000
	s_add_u32 s56, s34, s11
	s_addc_u32 s57, s35, 0
	s_add_i32 s11, s9, s1
	s_add_i32 s11, s11, 0x19402800
	s_add_u32 s58, s34, s11
	s_addc_u32 s59, s35, 0
	s_add_i32 s11, s9, s8
	s_add_i32 s11, s11, 0xa400000
	s_add_u32 s60, s34, s11
	s_addc_u32 s61, s35, 0
	s_lshl_b32 s23, s77, 12
	s_add_i32 s22, s9, s8
	s_add_i32 s22, s22, 0xa401800
	s_add_i32 s11, s9, s1
	s_add_i32 s11, s11, s23
	s_add_i32 s11, s11, 0x1c3ff800
	s_mov_b32 s83, 0xc000
	s_cmp_lt_u32 s76, 2
	s_cselect_b32 s11, s22, s11
	s_cselect_b32 s83, s83, 0x18000
	s_add_u32 s62, s34, s11
	s_addc_u32 s63, s35, 0
	s_add_i32 s11, s10, 0x3f2a000
	s_add_u32 s72, s34, s11
	s_addc_u32 s73, s35, 0
	s_add_i32 s11, s10, 0x4000
	s_add_u32 s74, s34, s11
	s_addc_u32 s75, s35, 0
	s_mov_b32 s80, 0
	v_mov_b32_e32 v132, 0x20000
	s_mov_b32 s82, 0
	s_cmp_lt_i32 s82, s80
	s_cbranch_scc1 .Lg2l_rdy_0
	s_add_i32 s0, s82, 16
	s_min_i32 s0, s0, 0x100
.Lg2l_fl_0:
	s_cmp_ge_i32 s80, s0
	s_cbranch_scc1 .Lg2l_acq_0
	s_mov_b32 s1, 0x4000
.Lg2l_poll_0:
	global_load_dword v130, v121, s[74:75] sc1
	s_waitcnt vmcnt(0)
	v_cmp_ne_u32_e32 vcc, 0, v130
	s_cbranch_vccnz .Lg2l_got_0
	s_sleep 8
	s_add_i32 s1, s1, -1
	s_cmp_lg_u32 s1, 0
	s_cbranch_scc1 .Lg2l_poll_0
.Lg2l_got_0:
	s_add_i32 s80, s80, 1
	s_add_u32 s74, s74, 24
	s_addc_u32 s75, s75, 0
	s_branch .Lg2l_fl_0

.Lg2l_rdy_0:
	global_load_dwordx4 v[0:3], v120, s[44:45]
	global_load_dwordx4 v[4:7], v120, s[46:47]
	global_load_dwordx4 v[8:11], v120, s[48:49]
	global_load_dwordx4 v[12:15], v120, s[50:51]
	global_load_dwordx4 v[16:19], v120, s[52:53]
	global_load_dwordx4 v[20:23], v120, s[54:55]
	global_load_dwordx4 v[24:27], v120, s[56:57]
	global_load_dwordx4 v[28:31], v120, s[58:59]
	global_load_dwordx4 v[32:35], v120, s[60:61]
	global_load_dwordx4 v[36:39], v120, s[62:63]
	global_load_dword v127, v121, s[72:73]
	s_add_u32 s44, s44, 0x18000
	s_addc_u32 s45, s45, 0
	s_add_u32 s46, s46, 0x18000
	s_addc_u32 s47, s47, 0
	s_add_u32 s48, s48, 0x18000
	s_addc_u32 s49, s49, 0
	s_add_u32 s50, s50, 0x18000
	s_addc_u32 s51, s51, 0
	s_add_u32 s52, s52, 0x18000
	s_addc_u32 s53, s53, 0
	s_add_u32 s54, s54, 0x18000
	s_addc_u32 s55, s55, 0
	s_add_u32 s56, s56, 0x18000
	s_addc_u32 s57, s57, 0
	s_add_u32 s58, s58, 0x18000
	s_addc_u32 s59, s59, 0
	s_add_u32 s60, s60, 0xc000
	s_addc_u32 s61, s61, 0
	s_add_u32 s62, s62, s83
	s_addc_u32 s63, s63, 0
	s_add_u32 s72, s72, 24
	s_addc_u32 s73, s73, 0
	s_mov_b32 s81, 0
	s_and_b32 s0, s81, 1
	v_lshl_add_u32 v131, s0, 16, v125
	s_waitcnt vmcnt(0)
	ds_write_b128 v131, v[0:3]
	ds_write_b128 v131, v[4:7] offset:6144
	ds_write_b128 v131, v[8:11] offset:12288
	ds_write_b128 v131, v[12:15] offset:18432
	ds_write_b128 v131, v[16:19] offset:24576
	ds_write_b128 v131, v[20:23] offset:30720
	ds_write_b128 v131, v[24:27] offset:36864
	ds_write_b128 v131, v[28:31] offset:43008
	ds_write_b128 v131, v[32:35] offset:49152
	ds_write_b128 v131, v[36:39] offset:55296
	s_and_saveexec_b64 s[8:9], s[6:7]
	s_cbranch_execz .Lg2l_nocd_1
	s_lshl_b32 s0, s0, 2
	v_add_u32_e32 v130, s0, v132
	ds_write_b32 v130, v127
.Lg2l_nocd_1:
	s_or_b64 exec, exec, s[8:9]
	global_load_dwordx4 v[0:3], v120, s[44:45]
	global_load_dwordx4 v[4:7], v120, s[46:47]
	global_load_dwordx4 v[8:11], v120, s[48:49]
	global_load_dwordx4 v[12:15], v120, s[50:51]
	global_load_dwordx4 v[16:19], v120, s[52:53]
	global_load_dwordx4 v[20:23], v120, s[54:55]
	global_load_dwordx4 v[24:27], v120, s[56:57]
	global_load_dwordx4 v[28:31], v120, s[58:59]
	global_load_dwordx4 v[32:35], v120, s[60:61]
	global_load_dwordx4 v[36:39], v120, s[62:63]
	global_load_dword v127, v121, s[72:73]
	s_add_u32 s44, s44, 0x18000
	s_addc_u32 s45, s45, 0
	s_add_u32 s46, s46, 0x18000
	s_addc_u32 s47, s47, 0
	s_add_u32 s48, s48, 0x18000
	s_addc_u32 s49, s49, 0
	s_add_u32 s50, s50, 0x18000
	s_addc_u32 s51, s51, 0
	s_add_u32 s52, s52, 0x18000
	s_addc_u32 s53, s53, 0
	s_add_u32 s54, s54, 0x18000
	s_addc_u32 s55, s55, 0
	s_add_u32 s56, s56, 0x18000
	s_addc_u32 s57, s57, 0
	s_add_u32 s58, s58, 0x18000
	s_addc_u32 s59, s59, 0
	s_add_u32 s60, s60, 0xc000
	s_addc_u32 s61, s61, 0
	s_add_u32 s62, s62, s83
	s_addc_u32 s63, s63, 0
	s_add_u32 s72, s72, 24
	s_addc_u32 s73, s73, 0
	global_load_dwordx4 v[40:43], v120, s[44:45]
	global_load_dwordx4 v[44:47], v120, s[46:47]
	global_load_dwordx4 v[48:51], v120, s[48:49]
	global_load_dwordx4 v[52:55], v120, s[50:51]
	global_load_dwordx4 v[56:59], v120, s[52:53]
	global_load_dwordx4 v[60:63], v120, s[54:55]
	global_load_dwordx4 v[64:67], v120, s[56:57]
	global_load_dwordx4 v[68:71], v120, s[58:59]
	global_load_dwordx4 v[72:75], v120, s[60:61]
	global_load_dwordx4 v[76:79], v120, s[62:63]
	global_load_dword v128, v121, s[72:73]
	s_add_u32 s44, s44, 0x18000
	s_addc_u32 s45, s45, 0
	s_add_u32 s46, s46, 0x18000
	s_addc_u32 s47, s47, 0
	s_add_u32 s48, s48, 0x18000
	s_addc_u32 s49, s49, 0
	s_add_u32 s50, s50, 0x18000
	s_addc_u32 s51, s51, 0
	s_add_u32 s52, s52, 0x18000
	s_addc_u32 s53, s53, 0
	s_add_u32 s54, s54, 0x18000
	s_addc_u32 s55, s55, 0
	s_add_u32 s56, s56, 0x18000
	s_addc_u32 s57, s57, 0
	s_add_u32 s58, s58, 0x18000
	s_addc_u32 s59, s59, 0
	s_add_u32 s60, s60, 0xc000
	s_addc_u32 s61, s61, 0
	s_add_u32 s62, s62, s83
	s_addc_u32 s63, s63, 0
	s_add_u32 s72, s72, 24
	s_addc_u32 s73, s73, 0
	global_load_dwordx4 v[80:83], v120, s[44:45]
	global_load_dwordx4 v[84:87], v120, s[46:47]
	global_load_dwordx4 v[88:91], v120, s[48:49]
	global_load_dwordx4 v[92:95], v120, s[50:51]
	global_load_dwordx4 v[96:99], v120, s[52:53]
	global_load_dwordx4 v[100:103], v120, s[54:55]
	global_load_dwordx4 v[104:107], v120, s[56:57]
	global_load_dwordx4 v[108:111], v120, s[58:59]
	global_load_dwordx4 v[112:115], v120, s[60:61]
	global_load_dwordx4 v[116:119], v120, s[62:63]
	global_load_dword v129, v121, s[72:73]
	s_add_u32 s44, s44, 0x18000
	s_addc_u32 s45, s45, 0
	s_add_u32 s46, s46, 0x18000
	s_addc_u32 s47, s47, 0
	s_add_u32 s48, s48, 0x18000
	s_addc_u32 s49, s49, 0
	s_add_u32 s50, s50, 0x18000
	s_addc_u32 s51, s51, 0
	s_add_u32 s52, s52, 0x18000
	s_addc_u32 s53, s53, 0
	s_add_u32 s54, s54, 0x18000
	s_addc_u32 s55, s55, 0
	s_add_u32 s56, s56, 0x18000
	s_addc_u32 s57, s57, 0
	s_add_u32 s58, s58, 0x18000
	s_addc_u32 s59, s59, 0
	s_add_u32 s60, s60, 0xc000
	s_addc_u32 s61, s61, 0
	s_add_u32 s62, s62, s83
	s_addc_u32 s63, s63, 0
	s_add_u32 s72, s72, 24
	s_addc_u32 s73, s73, 0
	s_waitcnt lgkmcnt(0)
	s_barrier
	s_mov_b32 s81, 1
.Lg2l_loop:
	s_cmpk_lt_u32 s81, 0xf0
	s_cbranch_scc0 .Lg2l_tail_2
	s_and_b32 s0, s81, 1
	v_lshl_add_u32 v131, s0, 16, v125
	s_waitcnt vmcnt(22)
	ds_write_b128 v131, v[0:3]
	ds_write_b128 v131, v[4:7] offset:6144
	ds_write_b128 v131, v[8:11] offset:12288
	ds_write_b128 v131, v[12:15] offset:18432
	ds_write_b128 v131, v[16:19] offset:24576
	ds_write_b128 v131, v[20:23] offset:30720
	ds_write_b128 v131, v[24:27] offset:36864
	ds_write_b128 v131, v[28:31] offset:43008
	ds_write_b128 v131, v[32:35] offset:49152
	ds_write_b128 v131, v[36:39] offset:55296
	s_and_saveexec_b64 s[8:9], s[6:7]
	s_cbranch_execz .Lg2l_nocd_3
	s_lshl_b32 s0, s0, 2
	v_add_u32_e32 v130, s0, v132
	ds_write_b32 v130, v127
.Lg2l_nocd_3:
	s_or_b64 exec, exec, s[8:9]
	s_branch .Lg2l_std_2
.Lg2l_tail_2:
	s_and_b32 s0, s81, 1
	v_lshl_add_u32 v131, s0, 16, v125
	s_waitcnt vmcnt(0)
	ds_write_b128 v131, v[0:3]
	ds_write_b128 v131, v[4:7] offset:6144
	ds_write_b128 v131, v[8:11] offset:12288
	ds_write_b128 v131, v[12:15] offset:18432
	ds_write_b128 v131, v[16:19] offset:24576
	ds_write_b128 v131, v[20:23] offset:30720
	ds_write_b128 v131, v[24:27] offset:36864
	ds_write_b128 v131, v[28:31] offset:43008
	ds_write_b128 v131, v[32:35] offset:49152
	ds_write_b128 v131, v[36:39] offset:55296
	s_and_saveexec_b64 s[8:9], s[6:7]
	s_cbranch_execz .Lg2l_nocd_4
	s_lshl_b32 s0, s0, 2
	v_add_u32_e32 v130, s0, v132
	ds_write_b32 v130, v127

.Lg2l_std_2:
	s_add_i32 s82, s81, 3
	s_cmpk_lt_u32 s82, 0x100
	s_cbranch_scc0 .Lg2l_nold_2
	s_cmp_lt_i32 s82, s80
	s_cbranch_scc1 .Lg2l_rdy_5
	s_add_i32 s0, s82, 16
	s_min_i32 s0, s0, 0x100

.Lg2l_rdy_5:
	global_load_dwordx4 v[0:3], v120, s[44:45]
	global_load_dwordx4 v[4:7], v120, s[46:47]
	global_load_dwordx4 v[8:11], v120, s[48:49]
	global_load_dwordx4 v[12:15], v120, s[50:51]
	global_load_dwordx4 v[16:19], v120, s[52:53]
	global_load_dwordx4 v[20:23], v120, s[54:55]
	global_load_dwordx4 v[24:27], v120, s[56:57]
	global_load_dwordx4 v[28:31], v120, s[58:59]
	global_load_dwordx4 v[32:35], v120, s[60:61]
	global_load_dwordx4 v[36:39], v120, s[62:63]
	global_load_dword v127, v121, s[72:73]
	s_add_u32 s44, s44, 0x18000
	s_addc_u32 s45, s45, 0
	s_add_u32 s46, s46, 0x18000
	s_addc_u32 s47, s47, 0
	s_add_u32 s48, s48, 0x18000
	s_addc_u32 s49, s49, 0
	s_add_u32 s50, s50, 0x18000
	s_addc_u32 s51, s51, 0
	s_add_u32 s52, s52, 0x18000
	s_addc_u32 s53, s53, 0
	s_add_u32 s54, s54, 0x18000
	s_addc_u32 s55, s55, 0
	s_add_u32 s56, s56, 0x18000
	s_addc_u32 s57, s57, 0
	s_add_u32 s58, s58, 0x18000
	s_addc_u32 s59, s59, 0
	s_add_u32 s60, s60, 0xc000
	s_addc_u32 s61, s61, 0
	s_add_u32 s62, s62, s83
	s_addc_u32 s63, s63, 0
	s_add_u32 s72, s72, 24
	s_addc_u32 s73, s73, 0
.Lg2l_nold_2:
	s_waitcnt lgkmcnt(0)
	s_barrier
	s_add_i32 s81, s81, 1
	s_cmpk_lt_u32 s81, 0x100
	s_cbranch_scc0 .Lg2l_exit
	s_cmpk_lt_u32 s81, 0xf0
	s_cbranch_scc0 .Lg2l_tail_6
	s_and_b32 s0, s81, 1
	v_lshl_add_u32 v131, s0, 16, v125
	s_waitcnt vmcnt(22)
	ds_write_b128 v131, v[40:43]
	ds_write_b128 v131, v[44:47] offset:6144
	ds_write_b128 v131, v[48:51] offset:12288
	ds_write_b128 v131, v[52:55] offset:18432
	ds_write_b128 v131, v[56:59] offset:24576
	ds_write_b128 v131, v[60:63] offset:30720
	ds_write_b128 v131, v[64:67] offset:36864
	ds_write_b128 v131, v[68:71] offset:43008
	ds_write_b128 v131, v[72:75] offset:49152
	ds_write_b128 v131, v[76:79] offset:55296
	s_and_saveexec_b64 s[8:9], s[6:7]
	s_cbranch_execz .Lg2l_nocd_7
	s_lshl_b32 s0, s0, 2
	v_add_u32_e32 v130, s0, v132
	ds_write_b32 v130, v128

.Lg2l_tail_6:
	s_and_b32 s0, s81, 1
	v_lshl_add_u32 v131, s0, 16, v125
	s_waitcnt vmcnt(0)
	ds_write_b128 v131, v[40:43]
	ds_write_b128 v131, v[44:47] offset:6144
	ds_write_b128 v131, v[48:51] offset:12288
	ds_write_b128 v131, v[52:55] offset:18432
	ds_write_b128 v131, v[56:59] offset:24576
	ds_write_b128 v131, v[60:63] offset:30720
	ds_write_b128 v131, v[64:67] offset:36864
	ds_write_b128 v131, v[68:71] offset:43008
	ds_write_b128 v131, v[72:75] offset:49152
	ds_write_b128 v131, v[76:79] offset:55296
	s_and_saveexec_b64 s[8:9], s[6:7]
	s_cbranch_execz .Lg2l_nocd_8
	s_lshl_b32 s0, s0, 2
	v_add_u32_e32 v130, s0, v132
	ds_write_b32 v130, v128

.Lg2l_rdy_9:
	global_load_dwordx4 v[40:43], v120, s[44:45]
	global_load_dwordx4 v[44:47], v120, s[46:47]
	global_load_dwordx4 v[48:51], v120, s[48:49]
	global_load_dwordx4 v[52:55], v120, s[50:51]
	global_load_dwordx4 v[56:59], v120, s[52:53]
	global_load_dwordx4 v[60:63], v120, s[54:55]
	global_load_dwordx4 v[64:67], v120, s[56:57]
	global_load_dwordx4 v[68:71], v120, s[58:59]
	global_load_dwordx4 v[72:75], v120, s[60:61]
	global_load_dwordx4 v[76:79], v120, s[62:63]
	global_load_dword v128, v121, s[72:73]
	s_add_u32 s44, s44, 0x18000
	s_addc_u32 s45, s45, 0
	s_add_u32 s46, s46, 0x18000
	s_addc_u32 s47, s47, 0
	s_add_u32 s48, s48, 0x18000
	s_addc_u32 s49, s49, 0
	s_add_u32 s50, s50, 0x18000
	s_addc_u32 s51, s51, 0
	s_add_u32 s52, s52, 0x18000
	s_addc_u32 s53, s53, 0
	s_add_u32 s54, s54, 0x18000
	s_addc_u32 s55, s55, 0
	s_add_u32 s56, s56, 0x18000
	s_addc_u32 s57, s57, 0
	s_add_u32 s58, s58, 0x18000
	s_addc_u32 s59, s59, 0
	s_add_u32 s60, s60, 0xc000
	s_addc_u32 s61, s61, 0
	s_add_u32 s62, s62, s83
	s_addc_u32 s63, s63, 0
	s_add_u32 s72, s72, 24
	s_addc_u32 s73, s73, 0
.Lg2l_nold_6:
	s_waitcnt lgkmcnt(0)
	s_barrier
	s_add_i32 s81, s81, 1
	s_cmpk_lt_u32 s81, 0x100
	s_cbranch_scc0 .Lg2l_exit
	s_cmpk_lt_u32 s81, 0xf0
	s_cbranch_scc0 .Lg2l_tail_10
	s_and_b32 s0, s81, 1
	v_lshl_add_u32 v131, s0, 16, v125
	s_waitcnt vmcnt(22)
	ds_write_b128 v131, v[80:83]
	ds_write_b128 v131, v[84:87] offset:6144
	ds_write_b128 v131, v[88:91] offset:12288
	ds_write_b128 v131, v[92:95] offset:18432
	ds_write_b128 v131, v[96:99] offset:24576
	ds_write_b128 v131, v[100:103] offset:30720
	ds_write_b128 v131, v[104:107] offset:36864
	ds_write_b128 v131, v[108:111] offset:43008
	ds_write_b128 v131, v[112:115] offset:49152
	ds_write_b128 v131, v[116:119] offset:55296
	s_and_saveexec_b64 s[8:9], s[6:7]
	s_cbranch_execz .Lg2l_nocd_11
	s_lshl_b32 s0, s0, 2
	v_add_u32_e32 v130, s0, v132
	ds_write_b32 v130, v129

.Lg2l_tail_10:
	s_and_b32 s0, s81, 1
	v_lshl_add_u32 v131, s0, 16, v125
	s_waitcnt vmcnt(0)
	ds_write_b128 v131, v[80:83]
	ds_write_b128 v131, v[84:87] offset:6144
	ds_write_b128 v131, v[88:91] offset:12288
	ds_write_b128 v131, v[92:95] offset:18432
	ds_write_b128 v131, v[96:99] offset:24576
	ds_write_b128 v131, v[100:103] offset:30720
	ds_write_b128 v131, v[104:107] offset:36864
	ds_write_b128 v131, v[108:111] offset:43008
	ds_write_b128 v131, v[112:115] offset:49152
	ds_write_b128 v131, v[116:119] offset:55296
	s_and_saveexec_b64 s[8:9], s[6:7]
	s_cbranch_execz .Lg2l_nocd_12
	s_lshl_b32 s0, s0, 2
	v_add_u32_e32 v130, s0, v132
	ds_write_b32 v130, v129

.Lg2l_rdy_13:
	global_load_dwordx4 v[80:83], v120, s[44:45]
	global_load_dwordx4 v[84:87], v120, s[46:47]
	global_load_dwordx4 v[88:91], v120, s[48:49]
	global_load_dwordx4 v[92:95], v120, s[50:51]
	global_load_dwordx4 v[96:99], v120, s[52:53]
	global_load_dwordx4 v[100:103], v120, s[54:55]
	global_load_dwordx4 v[104:107], v120, s[56:57]
	global_load_dwordx4 v[108:111], v120, s[58:59]
	global_load_dwordx4 v[112:115], v120, s[60:61]
	global_load_dwordx4 v[116:119], v120, s[62:63]
	global_load_dword v129, v121, s[72:73]
	s_add_u32 s44, s44, 0x18000
	s_addc_u32 s45, s45, 0
	s_add_u32 s46, s46, 0x18000
	s_addc_u32 s47, s47, 0
	s_add_u32 s48, s48, 0x18000
	s_addc_u32 s49, s49, 0
	s_add_u32 s50, s50, 0x18000
	s_addc_u32 s51, s51, 0
	s_add_u32 s52, s52, 0x18000
	s_addc_u32 s53, s53, 0
	s_add_u32 s54, s54, 0x18000
	s_addc_u32 s55, s55, 0
	s_add_u32 s56, s56, 0x18000
	s_addc_u32 s57, s57, 0
	s_add_u32 s58, s58, 0x18000
	s_addc_u32 s59, s59, 0
	s_add_u32 s60, s60, 0xc000
	s_addc_u32 s61, s61, 0
	s_add_u32 s62, s62, s83
	s_addc_u32 s63, s63, 0
	s_add_u32 s72, s72, 24
	s_addc_u32 s73, s73, 0
.Lg2l_nold_10:
	s_waitcnt lgkmcnt(0)
	s_barrier
	s_add_i32 s81, s81, 1
	s_cmpk_lt_u32 s81, 0x100
	s_cbranch_scc1 .Lg2l_loop
.Lg2l_exit:
	s_barrier
	s_branch .LBB0_1543
